# v30 + LayerNorm phases: 64-lane sums via DPP row all-reduce + row_bcast + readlane (bit-identical order) instead of 12 ds_bpermute round trips per row; LN weight/bias loaded once before the row loop;
# speedup vs baseline: 1.0183x; 1.0105x over previous
; DI void ln_phase(float* io, bf16* act, const float* w, const float* b, const bool wr_f32, const bool wr_bf16) {
;     ...
;     if (gw < T) { const f32x4* x0 = (const f32x4*)(io + (size_t)gw * D) + lane;
; #pragma unroll
;         for (int j = 0; j < 4; ++j) nv[j] = x0[64 * j]; }
;     for (int r = gw; r < T; r += ngw) {
;         f32x4* xr = (f32x4*)(io + (size_t)r * D) + lane; f32x4 v[4]; float s = 0.f;
; #pragma unroll
;         for (int j = 0; j < 4; ++j) { v[j] = nv[j]; s += (v[j][0] + v[j][1]) + (v[j][2] + v[j][3]); }
;         if (r + ngw < T) { const f32x4* xn = (const f32x4*)(io + (size_t)(r + ngw) * D) + lane;
; #pragma unroll
;             for (int j = 0; j < 4; ++j) nv[j] = xn[64 * j]; }
;         const float mean = wave_sum(s) * (1.f / D); float s2 = 0.f;
; #pragma unroll
;         for (int j = 0; j < 4; ++j) { v[j] = v[j] - mean; s2 += (v[j][0] * v[j][0] + v[j][1] * v[j][1]) + (v[j][2] * v[j][2] + v[j][3] * v[j][3]); }
;         const float rstd = 1.f / sqrtf(wave_sum(s2) * (1.f / D) + LN_EPS);
.LBB0_1110:
	s_or_b64 exec, exec, s[0:1]
	v_readlane_b32 s6, v252, 0
	v_readlane_b32 s7, v252, 1
	v_readlane_b32 s0, v254, 35
	s_waitcnt lgkmcnt(0)
	v_mov_b32_e32 v0, v232
	s_barrier
	s_lshl_b32 s90, s0, 10
	v_readlane_b32 s0, v252, 2
	v_ashrrev_i32_e32 v16, 6, v0
	v_readlane_b32 s1, v254, 36
	v_add_u32_e32 v32, s0, v16
	s_mov_b32 s0, 0x8000
	v_cmp_gt_i32_e32 vcc, s0, v32
	s_and_saveexec_b64 s[4:5], vcc
	s_cbranch_execz .LBB0_1115
	s_load_dwordx4 s[0:3], s[6:7], 0x118
	s_load_dwordx4 s[8:11], s[6:7], 0xe0
	v_ashrrev_i32_e32 v33, 31, v32
	v_and_b32_e32 v18, 63, v0
	v_lshlrev_b64 v[0:1], 12, v[32:33]
	v_lshlrev_b32_e32 v192, 4, v18
	s_waitcnt lgkmcnt(0)
	v_lshl_add_u64 v[0:1], s[0:1], 0, v[0:1]
	v_lshl_add_u64 v[0:1], v[0:1], 0, v[192:193]
	global_load_dwordx4 v[12:15], v[0:1], off
	global_load_dwordx4 v[8:11], v[0:1], off offset:1024
	global_load_dwordx4 v[4:7], v[0:1], off offset:2048
	s_nop 0
	global_load_dwordx4 v[0:3], v[0:1], off offset:3072
	v_and_b32_e32 v17, 64, v238
	v_add_u32_e32 v17, 64, v17
	v_xor_b32_e32 v19, 1, v238
	v_cmp_lt_i32_e32 vcc, v19, v17
	s_lshl_b64 s[6:7], s[90:91], 2
	s_add_u32 s10, s10, s6
	v_cndmask_b32_e32 v19, v238, v19, vcc
	v_lshlrev_b32_e32 v43, 2, v19
	v_xor_b32_e32 v19, 2, v238
	v_cmp_lt_i32_e32 vcc, v19, v17
	s_addc_u32 s11, s11, s7
	s_add_u32 s6, s8, s6
	v_cndmask_b32_e32 v19, v238, v19, vcc
	v_lshlrev_b32_e32 v44, 2, v19
	v_xor_b32_e32 v19, 4, v238
	v_cmp_lt_i32_e32 vcc, v19, v17
	s_addc_u32 s7, s9, s7
	v_lshl_add_u64 v[34:35], s[6:7], 0, v[192:193]
	v_cndmask_b32_e32 v19, v238, v19, vcc
	v_lshlrev_b32_e32 v45, 2, v19
	v_xor_b32_e32 v19, 8, v238
	v_cmp_lt_i32_e32 vcc, v19, v17
	v_readlane_b32 s6, v254, 3
	v_lshl_add_u64 v[36:37], s[10:11], 0, v[192:193]
	v_cndmask_b32_e32 v19, v238, v19, vcc
	v_lshlrev_b32_e32 v46, 2, v19
	v_xor_b32_e32 v19, 16, v238
	v_cmp_lt_i32_e32 vcc, v19, v17
	v_add_u32_e32 v16, s6, v16
	s_nop 0
	v_cndmask_b32_e32 v19, v238, v19, vcc
	v_lshlrev_b32_e32 v47, 2, v19
	v_xor_b32_e32 v19, 32, v238
	v_cmp_lt_i32_e32 vcc, v19, v17
	s_nop 1
	v_cndmask_b32_e32 v17, v238, v19, vcc
	v_lshlrev_b32_e32 v48, 2, v17
	v_ashrrev_i32_e32 v17, 31, v16
	v_lshlrev_b64 v[16:17], 12, v[16:17]
	v_or_b32_e32 v16, v16, v192
	v_lshl_add_u64 v[38:39], s[0:1], 0, v[16:17]
	v_lshlrev_b64 v[16:17], 11, v[32:33]
	v_lshl_or_b32 v16, v18, 3, v16
	v_lshl_add_u64 v[16:17], s[2:3], 0, v[16:17]
	s_mov_b64 s[0:1], 0x4000600
	v_lshl_add_u64 v[40:41], v[16:17], 0, s[0:1]
	s_mov_b64 s[2:3], 0
	global_load_dwordx4 v[64:67], v[34:35], off
	global_load_dwordx4 v[68:71], v[36:37], off
	global_load_dwordx4 v[72:75], v[34:35], off offset:1024
	global_load_dwordx4 v[76:79], v[36:37], off offset:1024
	global_load_dwordx4 v[80:83], v[34:35], off offset:2048
	global_load_dwordx4 v[84:87], v[36:37], off offset:2048
	global_load_dwordx4 v[88:91], v[34:35], off offset:3072
	global_load_dwordx4 v[92:95], v[36:37], off offset:3072
	s_waitcnt vmcnt(0)
	s_branch .LBB0_1113
.LBB0_1112:
	s_or_b64 exec, exec, s[6:7]
	v_add_f32_e32 v33, v12, v13
	v_add_f32_e32 v42, v14, v15
	v_add_f32_e32 v33, v33, v42
	v_add_f32_e32 v42, v8, v9
	v_add_f32_e32 v49, v10, v11
	v_add_f32_e32 v33, 0, v33
	v_add_f32_e32 v42, v42, v49
	v_add_f32_e32 v33, v42, v33
	v_add_f32_e32 v42, v4, v5
	v_add_f32_e32 v49, v6, v7
	v_add_f32_e32 v42, v42, v49
	v_add_f32_e32 v33, v42, v33
	v_add_f32_e32 v42, v0, v1
	v_add_f32_e32 v49, v2, v3
	v_add_f32_e32 v42, v42, v49
	v_add_f32_e32 v33, v42, v33
	s_and_b64 s[0:1], exec, vcc
	s_or_b64 s[2:3], s[0:1], s[2:3]
	s_mov_b32 s0, 0xf800000
	s_nop 1
	v_add_f32_dpp v33, v33, v33 quad_perm:[1,0,3,2] row_mask:0xf bank_mask:0xf
	s_nop 1
	v_add_f32_dpp v33, v33, v33 quad_perm:[2,3,0,1] row_mask:0xf bank_mask:0xf
	s_nop 1
	v_add_f32_dpp v33, v33, v33 row_half_mirror row_mask:0xf bank_mask:0xf
	s_nop 1
	v_add_f32_dpp v33, v33, v33 row_mirror row_mask:0xf bank_mask:0xf
	s_nop 1
	v_add_f32_dpp v33, v33, v33 row_bcast:15 row_mask:0xa bank_mask:0xf
	s_nop 1
	v_add_f32_dpp v33, v33, v33 row_bcast:31 row_mask:0xc bank_mask:0xf
	s_nop 1
	v_readlane_b32 s98, v33, 63
	s_nop 1
	v_mov_b32_e32 v33, s98
	v_fmac_f32_e32 v13, 0xba800000, v33
	v_fmac_f32_e32 v12, 0xba800000, v33
	v_fmac_f32_e32 v15, 0xba800000, v33
	v_fmac_f32_e32 v14, 0xba800000, v33
	v_pk_mul_f32 v[50:51], v[14:15], v[14:15]
	v_pk_mul_f32 v[52:53], v[12:13], v[12:13]
	v_fmac_f32_e32 v9, 0xba800000, v33
	v_pk_mov_b32 v[54:55], v[52:53], v[50:51] op_sel:[1,0]
	v_mov_b32_e32 v53, v51
	v_fmac_f32_e32 v8, 0xba800000, v33
	v_fmac_f32_e32 v11, 0xba800000, v33
	v_fmac_f32_e32 v10, 0xba800000, v33
	v_pk_add_f32 v[50:51], v[54:55], v[52:53]
	v_pk_mul_f32 v[52:53], v[10:11], v[10:11]
	v_pk_mul_f32 v[54:55], v[8:9], v[8:9]
	v_fmac_f32_e32 v4, 0xba800000, v33
	v_pk_mov_b32 v[56:57], v[54:55], v[52:53] op_sel:[1,0]
	v_mov_b32_e32 v55, v53
	v_fmac_f32_e32 v6, 0xba800000, v33
	v_fmac_f32_e32 v5, 0xba800000, v33
	v_mul_f32_e32 v42, v4, v4
	v_pk_add_f32 v[52:53], v[56:57], v[54:55]
	v_fmac_f32_e32 v7, 0xba800000, v33
	v_pk_fma_f32 v[54:55], v[4:5], v[4:5], v[42:43] op_sel_hi:[1,1,0]
; DI unsigned pk2(float lo, float hi) { const f32x2 v = {lo, hi}; const bf16x2_t b = __builtin_convertvector(v, bf16x2_t); return __builtin_bit_cast(unsigned, b); }
; DI void ln_phase(float* io, bf16* act, const float* w, const float* b, const bool wr_f32, const bool wr_bf16) {
;     ...
;     for (int r = gw; r < T; r += ngw) {
;         f32x4* xr = (f32x4*)(io + (size_t)r * D) + lane; f32x4 v[4]; float s = 0.f;
; #pragma unroll
;         for (int j = 0; j < 4; ++j) { v[j] = nv[j]; s += (v[j][0] + v[j][1]) + (v[j][2] + v[j][3]); }
;         if (r + ngw < T) { const f32x4* xn = (const f32x4*)(io + (size_t)(r + ngw) * D) + lane;
; #pragma unroll
;             for (int j = 0; j < 4; ++j) nv[j] = xn[64 * j]; }
;     ...
;         const float rstd = 1.f / sqrtf(wave_sum(s2) * (1.f / D) + LN_EPS);
;         v2u* o8 = (v2u*)(act + (size_t)r * D) + lane;
; #pragma unroll
;         for (int j = 0; j < 4; ++j) { const f32x4 wv = ((const f32x4*)w)[lane + 64 * j], bv = ((const f32x4*)b)[lane + 64 * j];
;             f32x4 y; y[0] = v[j][0] * rstd * wv[0] + bv[0]; y[1] = v[j][1] * rstd * wv[1] + bv[1]; y[2] = v[j][2] * rstd * wv[2] + bv[2]; y[3] = v[j][3] * rstd * wv[3] + bv[3];
;             if (wr_f32) xr[64 * j] = y; if (wr_bf16) { v2u p; p.x = pk2(y[0], y[1]); p.y = pk2(y[2], y[3]); o8[64 * j] = p; } }
	v_mul_f32_e32 v42, v6, v6
	v_pk_add_f32 v[50:51], v[50:51], v[50:51] op_sel_hi:[0,1]
	v_pk_add_f32 v[52:53], v[52:53], v[52:53] op_sel_hi:[0,1]
	v_pk_fma_f32 v[56:57], v[6:7], v[6:7], v[42:43] op_sel_hi:[1,1,0]
	v_fmac_f32_e32 v3, 0xba800000, v33
	v_fmac_f32_e32 v2, 0xba800000, v33
	v_fmac_f32_e32 v1, 0xba800000, v33
	v_fmac_f32_e32 v0, 0xba800000, v33
	v_mul_f32_e32 v54, v0, v0
	v_mul_f32_e32 v56, v1, v1
	v_mul_f32_e32 v50, v2, v2
	v_mul_f32_e32 v52, v3, v3
	v_pk_add_f32 v[54:55], v[54:55], v[56:57]
	v_pk_add_f32 v[50:51], v[50:51], v[52:53]
	s_nop 0
	v_pk_add_f32 v[50:51], v[54:55], v[50:51]
	s_nop 0
	v_add_f32_e32 v33, v50, v51
	s_nop 1
	v_add_f32_dpp v33, v33, v33 quad_perm:[1,0,3,2] row_mask:0xf bank_mask:0xf
	s_nop 1
	v_add_f32_dpp v33, v33, v33 quad_perm:[2,3,0,1] row_mask:0xf bank_mask:0xf
	s_nop 1
	v_add_f32_dpp v33, v33, v33 row_half_mirror row_mask:0xf bank_mask:0xf
	s_nop 1
	v_add_f32_dpp v33, v33, v33 row_mirror row_mask:0xf bank_mask:0xf
	s_nop 1
	v_add_f32_dpp v33, v33, v33 row_bcast:15 row_mask:0xa bank_mask:0xf
	s_nop 1
	v_add_f32_dpp v33, v33, v33 row_bcast:31 row_mask:0xc bank_mask:0xf
	s_nop 1
	v_readlane_b32 s98, v33, 63
	s_nop 1
	v_mov_b32_e32 v33, s98
	v_fmamk_f32 v33, v33, 0x3a800000, v235
	v_cmp_gt_f32_e32 vcc, s0, v33
	v_mul_f32_e32 v42, 0x4f800000, v33
	s_nop 0
	v_cndmask_b32_e32 v33, v33, v42, vcc
	v_sqrt_f32_e32 v42, v33
	s_nop 0
	v_add_u32_e32 v49, -1, v42
	v_fma_f32 v50, -v49, v42, v33
	v_cmp_ge_f32_e64 s[0:1], 0, v50
	v_add_u32_e32 v50, 1, v42
	s_nop 0
	v_cndmask_b32_e64 v49, v42, v49, s[0:1]
	v_fma_f32 v42, -v50, v42, v33
	v_cmp_lt_f32_e64 s[0:1], 0, v42
	s_nop 1
	v_cndmask_b32_e64 v42, v49, v50, s[0:1]
	v_mul_f32_e32 v49, 0x37800000, v42
	v_cndmask_b32_e32 v42, v42, v49, vcc
	v_cmp_class_f32_e32 vcc, v33, v234
	s_nop 1
	v_cndmask_b32_e32 v33, v42, v33, vcc
	v_div_scale_f32 v42, s[0:1], v33, v33, 1.0
	v_rcp_f32_e32 v49, v42
	v_readlane_b32 s0, v254, 15
	v_readlane_b32 s1, v254, 16
	v_fma_f32 v50, -v42, v49, 1.0
	v_fmac_f32_e32 v49, v50, v49
	v_div_scale_f32 v50, vcc, 1.0, v33, 1.0
	v_mul_f32_e32 v51, v50, v49
	v_fma_f32 v52, -v42, v51, v50
	v_fmac_f32_e32 v51, v52, v49
	v_fma_f32 v42, -v42, v51, v50
	v_div_fmas_f32 v42, v42, v49, v51
	v_div_fixup_f32 v42, v42, v33, 1.0
	v_pk_mul_f32 v[12:13], v[12:13], v[42:43] op_sel_hi:[1,0]
	v_pk_mul_f32 v[14:15], v[14:15], v[42:43] op_sel_hi:[1,0]
	v_pk_mul_f32 v[8:9], v[8:9], v[42:43] op_sel_hi:[1,0]
	v_pk_mul_f32 v[10:11], v[10:11], v[42:43] op_sel_hi:[1,0]
	v_pk_mul_f32 v[4:5], v[4:5], v[42:43] op_sel_hi:[1,0]
	v_pk_mul_f32 v[6:7], v[6:7], v[42:43] op_sel_hi:[1,0]
	v_pk_mul_f32 v[0:1], v[0:1], v[42:43] op_sel_hi:[1,0]
	v_pk_mul_f32 v[2:3], v[2:3], v[42:43] op_sel_hi:[1,0]
	v_lshl_add_u64 v[38:39], v[38:39], 0, s[0:1]
	v_readlane_b32 s0, v254, 17
	v_readlane_b32 s1, v254, 18
	v_pk_fma_f32 v[12:13], v[64:65], v[12:13], v[68:69]
	v_pk_fma_f32 v[14:15], v[66:67], v[14:15], v[70:71]
	v_cvt_pk_bf16_f32 v12, v12, v13
	v_cvt_pk_bf16_f32 v13, v14, v15
	global_store_dwordx2 v[40:41], v[12:13], off offset:-1536
	s_nop 0
	v_pk_fma_f32 v[8:9], v[72:73], v[8:9], v[76:77]
	v_pk_fma_f32 v[10:11], v[74:75], v[10:11], v[78:79]
	v_cvt_pk_bf16_f32 v8, v8, v9
	v_cvt_pk_bf16_f32 v9, v10, v11
	global_store_dwordx2 v[40:41], v[8:9], off offset:-1024
	s_nop 0
	v_pk_fma_f32 v[4:5], v[80:81], v[4:5], v[84:85]
	v_pk_fma_f32 v[6:7], v[82:83], v[6:7], v[86:87]
	v_cvt_pk_bf16_f32 v4, v4, v5
	v_cvt_pk_bf16_f32 v5, v6, v7
	global_store_dwordx2 v[40:41], v[4:5], off offset:-512
	s_nop 0
	s_waitcnt vmcnt(3)
	v_mov_b32_e32 v12, v20
	v_mov_b32_e32 v13, v21
	v_mov_b32_e32 v14, v22
	v_mov_b32_e32 v15, v23
	v_pk_fma_f32 v[0:1], v[88:89], v[0:1], v[92:93]
	v_pk_fma_f32 v[2:3], v[90:91], v[2:3], v[94:95]
	v_cvt_pk_bf16_f32 v0, v0, v1
	v_cvt_pk_bf16_f32 v1, v2, v3
	global_store_dwordx2 v[40:41], v[0:1], off
	v_lshl_add_u64 v[40:41], v[40:41], 0, s[0:1]
	v_mov_b32_e32 v8, v24
	v_mov_b32_e32 v9, v25
	v_mov_b32_e32 v10, v26
	v_mov_b32_e32 v11, v27
	v_mov_b32_e32 v4, v28
	v_mov_b32_e32 v5, v29
	v_mov_b32_e32 v6, v30
	v_mov_b32_e32 v7, v31
	v_mov_b32_e32 v0, v16
	v_mov_b32_e32 v1, v17
	v_mov_b32_e32 v2, v18
	v_mov_b32_e32 v3, v19
	s_andn2_b64 exec, exec, s[2:3]
	s_cbranch_execz .LBB0_1115
.LBB0_1113:
	v_add_u32_e32 v32, s78, v32
	s_mov_b32 s0, 0x8000
	s_movk_i32 s6, 0x7fff
	v_cmp_gt_i32_e64 s[0:1], s0, v32
	v_cmp_lt_i32_e32 vcc, s6, v32
	v_mov_b32_e32 v20, v12
	v_mov_b32_e32 v21, v13
	v_mov_b32_e32 v22, v14
	v_mov_b32_e32 v23, v15
	v_mov_b32_e32 v24, v8
	v_mov_b32_e32 v25, v9
	v_mov_b32_e32 v26, v10
	v_mov_b32_e32 v27, v11
	v_mov_b32_e32 v28, v4
	v_mov_b32_e32 v29, v5
	v_mov_b32_e32 v30, v6
	v_mov_b32_e32 v31, v7
	v_mov_b32_e32 v16, v0
	v_mov_b32_e32 v17, v1
	v_mov_b32_e32 v18, v2
	v_mov_b32_e32 v19, v3
	s_and_saveexec_b64 s[6:7], s[0:1]
	s_cbranch_execz .LBB0_1112
	global_load_dwordx4 v[20:23], v[38:39], off
	global_load_dwordx4 v[24:27], v[38:39], off offset:1024
	global_load_dwordx4 v[28:31], v[38:39], off offset:2048
	global_load_dwordx4 v[16:19], v[38:39], off offset:3072
	s_branch .LBB0_1112

; DI void ln_phase(float* io, bf16* act, const float* w, const float* b, const bool wr_f32, const bool wr_bf16) {
;     ...
;     if (gw < T) { const f32x4* x0 = (const f32x4*)(io + (size_t)gw * D) + lane;
; #pragma unroll
;         for (int j = 0; j < 4; ++j) nv[j] = x0[64 * j]; }
;     for (int r = gw; r < T; r += ngw) {
;         f32x4* xr = (f32x4*)(io + (size_t)r * D) + lane; f32x4 v[4]; float s = 0.f;
; #pragma unroll
;         for (int j = 0; j < 4; ++j) { v[j] = nv[j]; s += (v[j][0] + v[j][1]) + (v[j][2] + v[j][3]); }
;         if (r + ngw < T) { const f32x4* xn = (const f32x4*)(io + (size_t)(r + ngw) * D) + lane;
; #pragma unroll
;             for (int j = 0; j < 4; ++j) nv[j] = xn[64 * j]; }
.LBB0_1311:
	s_or_b64 exec, exec, s[0:1]
	v_readlane_b32 s10, v252, 0
	v_readlane_b32 s11, v252, 1
	s_waitcnt lgkmcnt(0)
	v_mov_b32_e32 v0, v232
	s_barrier
	v_readlane_b32 s0, v252, 2
	v_ashrrev_i32_e32 v12, 6, v0
	s_nop 0
	v_add_u32_e32 v32, s0, v12
	s_mov_b32 s0, 0x8000
	v_cmp_gt_i32_e32 vcc, s0, v32
	s_and_saveexec_b64 s[8:9], vcc
	s_cbranch_execz .LBB0_1324
	s_load_dwordx8 s[0:7], s[10:11], 0x108
	v_ashrrev_i32_e32 v33, 31, v32
	v_and_b32_e32 v14, 63, v0
	v_lshlrev_b64 v[0:1], 12, v[32:33]
	v_lshlrev_b32_e32 v192, 4, v14
	s_waitcnt lgkmcnt(0)
	v_lshl_add_u64 v[34:35], s[4:5], 0, v[0:1]
	v_lshl_add_u64 v[0:1], v[34:35], 0, v[192:193]
	global_load_dwordx4 v[28:31], v[0:1], off
	global_load_dwordx4 v[8:11], v[0:1], off offset:1024
	global_load_dwordx4 v[4:7], v[0:1], off offset:2048
	s_nop 0
	global_load_dwordx4 v[0:3], v[0:1], off offset:3072
	v_and_b32_e32 v13, 64, v238
	v_add_u32_e32 v13, 64, v13
	v_xor_b32_e32 v15, 1, v238
	v_cmp_lt_i32_e32 vcc, v15, v13
	s_lshl_b64 s[10:11], s[90:91], 2
	s_add_u32 s2, s2, s10
	v_cndmask_b32_e32 v15, v238, v15, vcc
	v_lshlrev_b32_e32 v48, 2, v15
	v_xor_b32_e32 v15, 2, v238
	v_cmp_lt_i32_e32 vcc, v15, v13
	s_addc_u32 s3, s3, s11
	s_add_u32 s0, s0, s10
	v_cndmask_b32_e32 v15, v238, v15, vcc
	v_lshlrev_b32_e32 v49, 2, v15
	v_xor_b32_e32 v15, 4, v238
	v_cmp_lt_i32_e32 vcc, v15, v13
	s_addc_u32 s1, s1, s11
	v_lshl_add_u64 v[36:37], s[0:1], 0, v[192:193]
	v_cndmask_b32_e32 v15, v238, v15, vcc
	v_lshlrev_b32_e32 v50, 2, v15
	v_xor_b32_e32 v15, 8, v238
	v_cmp_lt_i32_e32 vcc, v15, v13
	v_readlane_b32 s0, v254, 3
	v_lshl_add_u64 v[38:39], s[2:3], 0, v[192:193]
	v_cndmask_b32_e32 v15, v238, v15, vcc
	v_lshlrev_b32_e32 v51, 2, v15
	v_xor_b32_e32 v15, 16, v238
	v_cmp_lt_i32_e32 vcc, v15, v13
	v_add_u32_e32 v12, s0, v12
	s_mov_b64 s[0:1], 0x4000000
	v_cndmask_b32_e32 v15, v238, v15, vcc
	v_lshlrev_b32_e32 v52, 2, v15
	v_xor_b32_e32 v15, 32, v238
	v_cmp_lt_i32_e32 vcc, v15, v13
	s_nop 1
	v_cndmask_b32_e32 v13, v238, v15, vcc
	v_lshlrev_b32_e32 v53, 2, v13
	v_ashrrev_i32_e32 v13, 31, v12
	v_lshlrev_b64 v[12:13], 12, v[12:13]
	v_lshl_add_u64 v[40:41], s[4:5], 0, v[12:13]
	v_lshlrev_b64 v[12:13], 11, v[32:33]
	v_lshl_or_b32 v12, v14, 3, v12
	v_lshl_add_u64 v[12:13], s[6:7], 0, v[12:13]
	v_lshl_add_u64 v[42:43], v[12:13], 0, s[0:1]
	s_mov_b64 s[4:5], 0
	global_load_dwordx4 v[64:67], v[36:37], off
	global_load_dwordx4 v[68:71], v[38:39], off
	global_load_dwordx4 v[72:75], v[36:37], off offset:1024
	global_load_dwordx4 v[76:79], v[38:39], off offset:1024
	global_load_dwordx4 v[80:83], v[36:37], off offset:2048
	global_load_dwordx4 v[84:87], v[38:39], off offset:2048
	global_load_dwordx4 v[88:91], v[36:37], off offset:3072
	global_load_dwordx4 v[92:95], v[38:39], off offset:3072
	s_waitcnt vmcnt(0)
	s_branch .LBB0_1314
.LBB0_1313:
	s_and_b64 s[0:1], exec, s[0:1]
	s_or_b64 s[4:5], s[0:1], s[4:5]
	v_readlane_b32 s0, v254, 15
	v_readlane_b32 s2, v254, 17
	v_readlane_b32 s1, v254, 16
	v_readlane_b32 s3, v254, 18
	s_waitcnt vmcnt(4)
	v_mov_b32_e32 v28, v12
	v_lshl_add_u64 v[40:41], v[40:41], 0, s[0:1]
	v_lshl_add_u64 v[42:43], v[42:43], 0, s[2:3]
	v_lshl_add_u64 v[34:35], v[34:35], 0, s[0:1]
	v_mov_b32_e32 v29, v13
	v_mov_b32_e32 v30, v14
	v_mov_b32_e32 v31, v15
	v_mov_b32_e32 v8, v16
	v_mov_b32_e32 v9, v17
	v_mov_b32_e32 v10, v18
	v_mov_b32_e32 v11, v19
	v_mov_b32_e32 v4, v20
	v_mov_b32_e32 v5, v21
	v_mov_b32_e32 v6, v22
	v_mov_b32_e32 v7, v23
	v_mov_b32_e32 v0, v24
	v_mov_b32_e32 v1, v25
	v_mov_b32_e32 v2, v26
	v_mov_b32_e32 v3, v27
	s_andn2_b64 exec, exec, s[4:5]
	s_cbranch_execz .LBB0_1324
.LBB0_1314:
	v_add_u32_e32 v32, s78, v32
	s_mov_b32 s0, 0x8000
	v_cmp_gt_i32_e32 vcc, s0, v32
	s_movk_i32 s0, 0x7fff
	v_cmp_lt_i32_e64 s[0:1], s0, v32
	v_mov_b32_e32 v12, v28
	v_mov_b32_e32 v13, v29
	v_mov_b32_e32 v14, v30
	v_mov_b32_e32 v15, v31
	v_mov_b32_e32 v16, v8
	v_mov_b32_e32 v17, v9
	v_mov_b32_e32 v18, v10
	v_mov_b32_e32 v19, v11
	v_mov_b32_e32 v20, v4
	v_mov_b32_e32 v21, v5
	v_mov_b32_e32 v22, v6
	v_mov_b32_e32 v23, v7
	v_mov_b32_e32 v24, v0
	v_mov_b32_e32 v25, v1
	v_mov_b32_e32 v26, v2
	v_mov_b32_e32 v27, v3
	s_and_saveexec_b64 s[2:3], vcc
	s_cbranch_execz .LBB0_1316
	v_lshl_add_u64 v[24:25], v[40:41], 0, v[192:193]
	global_load_dwordx4 v[12:15], v[24:25], off
	global_load_dwordx4 v[16:19], v[24:25], off offset:1024
	global_load_dwordx4 v[20:23], v[24:25], off offset:2048
	s_nop 0
	global_load_dwordx4 v[24:27], v[24:25], off offset:3072
; DI unsigned pk2(float lo, float hi) { const f32x2 v = {lo, hi}; const bf16x2_t b = __builtin_convertvector(v, bf16x2_t); return __builtin_bit_cast(unsigned, b); }
; DI void ln_phase(float* io, bf16* act, const float* w, const float* b, const bool wr_f32, const bool wr_bf16) {
;     ...
;         const float mean = wave_sum(s) * (1.f / D); float s2 = 0.f;
; #pragma unroll
;         for (int j = 0; j < 4; ++j) { v[j] = v[j] - mean; s2 += (v[j][0] * v[j][0] + v[j][1] * v[j][1]) + (v[j][2] * v[j][2] + v[j][3] * v[j][3]); }
;         const float rstd = 1.f / sqrtf(wave_sum(s2) * (1.f / D) + LN_EPS);
;         v2u* o8 = (v2u*)(act + (size_t)r * D) + lane;
; #pragma unroll
;         for (int j = 0; j < 4; ++j) { const f32x4 wv = ((const f32x4*)w)[lane + 64 * j], bv = ((const f32x4*)b)[lane + 64 * j];
;             f32x4 y; y[0] = v[j][0] * rstd * wv[0] + bv[0]; y[1] = v[j][1] * rstd * wv[1] + bv[1]; y[2] = v[j][2] * rstd * wv[2] + bv[2]; y[3] = v[j][3] * rstd * wv[3] + bv[3];
;             if (wr_f32) xr[64 * j] = y; if (wr_bf16) { v2u p; p.x = pk2(y[0], y[1]); p.y = pk2(y[2], y[3]); o8[64 * j] = p; } }
.LBB0_1316:
	s_or_b64 exec, exec, s[2:3]
	v_add_f32_e32 v33, v28, v29
	v_add_f32_e32 v44, v30, v31
	v_add_f32_e32 v33, v33, v44
	v_add_f32_e32 v44, v8, v9
	v_add_f32_e32 v45, v10, v11
	v_add_f32_e32 v33, 0, v33
	v_add_f32_e32 v44, v44, v45
	v_add_f32_e32 v33, v44, v33
	v_add_f32_e32 v44, v4, v5
	v_add_f32_e32 v45, v6, v7
	v_add_f32_e32 v44, v44, v45
	v_add_f32_e32 v33, v44, v33
	v_add_f32_e32 v44, v0, v1
	v_add_f32_e32 v45, v2, v3
	v_add_f32_e32 v44, v44, v45
	v_add_f32_e32 v33, v44, v33
	s_mov_b32 s2, 0xf800000
	v_readlane_b32 s6, v254, 19
	v_readlane_b32 s7, v254, 20
	v_lshl_add_u64 v[44:45], v[34:35], 0, v[192:193]
	s_nop 1
	v_add_f32_dpp v33, v33, v33 quad_perm:[1,0,3,2] row_mask:0xf bank_mask:0xf
	s_nop 1
	v_add_f32_dpp v33, v33, v33 quad_perm:[2,3,0,1] row_mask:0xf bank_mask:0xf
	s_nop 1
	v_add_f32_dpp v33, v33, v33 row_half_mirror row_mask:0xf bank_mask:0xf
	s_nop 1
	v_add_f32_dpp v33, v33, v33 row_mirror row_mask:0xf bank_mask:0xf
	s_nop 1
	v_add_f32_dpp v33, v33, v33 row_bcast:15 row_mask:0xa bank_mask:0xf
	s_nop 1
	v_add_f32_dpp v33, v33, v33 row_bcast:31 row_mask:0xc bank_mask:0xf
	s_nop 1
	v_readlane_b32 s98, v33, 63
	s_nop 1
	v_mov_b32_e32 v33, s98
	v_fmac_f32_e32 v29, 0xba800000, v33
	v_fmac_f32_e32 v28, 0xba800000, v33
	v_fmac_f32_e32 v31, 0xba800000, v33
	v_fmac_f32_e32 v30, 0xba800000, v33
	v_pk_mul_f32 v[46:47], v[30:31], v[30:31]
	v_pk_mul_f32 v[54:55], v[28:29], v[28:29]
	v_fmac_f32_e32 v11, 0xba800000, v33
	v_pk_mov_b32 v[56:57], v[54:55], v[46:47] op_sel:[1,0]
	v_mov_b32_e32 v55, v47
	v_pk_add_f32 v[46:47], v[56:57], v[54:55]
	v_fmac_f32_e32 v10, 0xba800000, v33
	v_fmac_f32_e32 v9, 0xba800000, v33
	v_fmac_f32_e32 v8, 0xba800000, v33
	v_pk_add_f32 v[46:47], v[46:47], v[46:47] op_sel_hi:[0,1]
	v_pk_mul_f32 v[54:55], v[10:11], v[10:11]
	v_pk_mul_f32 v[56:57], v[8:9], v[8:9]
	v_fmac_f32_e32 v4, 0xba800000, v33
	v_pk_mov_b32 v[58:59], v[56:57], v[54:55] op_sel:[1,0]
	v_mov_b32_e32 v57, v55
	v_fmac_f32_e32 v6, 0xba800000, v33
	v_fmac_f32_e32 v5, 0xba800000, v33
	v_mul_f32_e32 v46, v4, v4
	v_pk_add_f32 v[54:55], v[58:59], v[56:57]
	v_fmac_f32_e32 v7, 0xba800000, v33
	v_pk_fma_f32 v[56:57], v[4:5], v[4:5], v[46:47] op_sel_hi:[1,1,0]
	v_mul_f32_e32 v46, v6, v6
	v_pk_add_f32 v[54:55], v[54:55], v[54:55] op_sel_hi:[0,1]
	v_pk_fma_f32 v[58:59], v[6:7], v[6:7], v[46:47] op_sel_hi:[1,1,0]
	v_fmac_f32_e32 v3, 0xba800000, v33
	v_fmac_f32_e32 v2, 0xba800000, v33
	v_fmac_f32_e32 v1, 0xba800000, v33
	v_fmac_f32_e32 v0, 0xba800000, v33
	v_mul_f32_e32 v56, v0, v0
	v_mul_f32_e32 v58, v1, v1
	v_mul_f32_e32 v46, v2, v2
	v_mul_f32_e32 v54, v3, v3
	v_pk_add_f32 v[56:57], v[56:57], v[58:59]
	v_pk_add_f32 v[46:47], v[46:47], v[54:55]
	s_nop 0
	v_pk_add_f32 v[46:47], v[56:57], v[46:47]
	s_nop 0
	v_add_f32_e32 v33, v46, v47
	s_nop 1
	v_add_f32_dpp v33, v33, v33 quad_perm:[1,0,3,2] row_mask:0xf bank_mask:0xf
	s_nop 1
	v_add_f32_dpp v33, v33, v33 quad_perm:[2,3,0,1] row_mask:0xf bank_mask:0xf
	s_nop 1
	v_add_f32_dpp v33, v33, v33 row_half_mirror row_mask:0xf bank_mask:0xf
	s_nop 1
	v_add_f32_dpp v33, v33, v33 row_mirror row_mask:0xf bank_mask:0xf
	s_nop 1
	v_add_f32_dpp v33, v33, v33 row_bcast:15 row_mask:0xa bank_mask:0xf
	s_nop 1
	v_add_f32_dpp v33, v33, v33 row_bcast:31 row_mask:0xc bank_mask:0xf
	s_nop 1
	v_readlane_b32 s98, v33, 63
	s_nop 1
	v_mov_b32_e32 v33, s98
	v_fmamk_f32 v33, v33, 0x3a800000, v235
	v_cmp_gt_f32_e32 vcc, s2, v33
	v_mul_f32_e32 v46, 0x4f800000, v33
	s_nop 0
	v_cndmask_b32_e32 v33, v33, v46, vcc
	v_sqrt_f32_e32 v46, v33
	s_nop 0
	v_add_u32_e32 v47, -1, v46
	v_fma_f32 v54, -v47, v46, v33
	v_cmp_ge_f32_e64 s[2:3], 0, v54
	v_add_u32_e32 v54, 1, v46
	s_nop 0
	v_cndmask_b32_e64 v47, v46, v47, s[2:3]
	v_fma_f32 v46, -v54, v46, v33
	v_cmp_lt_f32_e64 s[2:3], 0, v46
	s_nop 1
	v_cndmask_b32_e64 v46, v47, v54, s[2:3]
	v_mul_f32_e32 v47, 0x37800000, v46
	v_cndmask_b32_e32 v46, v46, v47, vcc
	v_cmp_class_f32_e32 vcc, v33, v234
	s_nop 1
	v_cndmask_b32_e32 v33, v46, v33, vcc
	v_div_scale_f32 v46, s[2:3], v33, v33, 1.0
	v_rcp_f32_e32 v47, v46
	s_nop 0
	v_fma_f32 v54, -v46, v47, 1.0
	v_fmac_f32_e32 v47, v54, v47
	v_div_scale_f32 v54, vcc, 1.0, v33, 1.0
	v_mul_f32_e32 v55, v54, v47
	v_fma_f32 v56, -v46, v55, v54
	v_fmac_f32_e32 v55, v56, v47
	v_fma_f32 v46, -v46, v55, v54
	v_div_fmas_f32 v46, v46, v47, v55
	v_div_fixup_f32 v46, v46, v33, 1.0
	v_pk_mul_f32 v[28:29], v[28:29], v[46:47] op_sel_hi:[1,0]
	v_pk_mul_f32 v[30:31], v[30:31], v[46:47] op_sel_hi:[1,0]
	v_cndmask_b32_e64 v33, 0, 1, s[6:7]
	v_cmp_ne_u32_e64 s[2:3], 1, v33
	s_andn2_b64 vcc, exec, s[6:7]
	v_pk_fma_f32 v[28:29], v[64:65], v[28:29], v[68:69]
	v_pk_fma_f32 v[30:31], v[66:67], v[30:31], v[70:71]
	global_store_dwordx4 v[44:45], v[28:31], off
	s_cbranch_vccnz .LBB0_1318
	s_nop 0
	v_cvt_pk_bf16_f32 v28, v28, v29
	v_cvt_pk_bf16_f32 v29, v30, v31
	global_store_dwordx2 v[42:43], v[28:29], off
.LBB0_1318:
	s_nop 0
	v_mov_b32_e32 v47, v46
	v_pk_mul_f32 v[8:9], v[8:9], v[46:47]
	v_pk_mul_f32 v[10:11], v[10:11], v[46:47]
	s_and_b64 vcc, exec, s[2:3]
	v_pk_fma_f32 v[8:9], v[8:9], v[72:73], v[76:77]
	v_pk_fma_f32 v[10:11], v[10:11], v[74:75], v[78:79]
	global_store_dwordx4 v[44:45], v[8:11], off offset:1024
	s_cbranch_vccnz .LBB0_1320
	s_nop 0
	v_cvt_pk_bf16_f32 v8, v8, v9
	v_cvt_pk_bf16_f32 v9, v10, v11
	global_store_dwordx2 v[42:43], v[8:9], off offset:512
.LBB0_1320:
	s_nop 0
	v_pk_mul_f32 v[4:5], v[4:5], v[46:47]
	v_pk_mul_f32 v[6:7], v[6:7], v[46:47]
	s_and_b64 vcc, exec, s[2:3]
	v_pk_fma_f32 v[4:5], v[4:5], v[80:81], v[84:85]
	v_pk_fma_f32 v[6:7], v[6:7], v[82:83], v[86:87]
	global_store_dwordx4 v[44:45], v[4:7], off offset:2048
	s_cbranch_vccnz .LBB0_1322
	s_nop 0
	v_cvt_pk_bf16_f32 v4, v4, v5
	v_cvt_pk_bf16_f32 v5, v6, v7
	global_store_dwordx2 v[42:43], v[4:5], off offset:1024
.LBB0_1322:
	s_nop 0
	v_pk_mul_f32 v[0:1], v[0:1], v[46:47]
	v_pk_mul_f32 v[2:3], v[2:3], v[46:47]
	s_and_b64 vcc, exec, s[2:3]
	v_pk_fma_f32 v[0:1], v[0:1], v[88:89], v[92:93]
	v_pk_fma_f32 v[2:3], v[2:3], v[90:91], v[94:95]
	global_store_dwordx4 v[44:45], v[0:3], off offset:3072
	s_cbranch_vccnz .LBB0_1313
	s_nop 0
	v_cvt_pk_bf16_f32 v0, v0, v1
	v_cvt_pk_bf16_f32 v1, v2, v3
	global_store_dwordx2 v[42:43], v[0:1], off offset:1536
	s_branch .LBB0_1313
